# SwiGLU GEMM epilogue: the 64 silu(gate)*up chains re-emitted eight at a time, interleaved, without the s_nop pads (same operations per element)
# baseline (speedup 1.0000x reference)
.LBB0_147:
	s_add_u32 s18, s16, 0xfffc0080
	s_addc_u32 s19, s17, -1
	s_add_i32 s83, 0, 0x10000
	v_add_u32_e32 v140, s83, v143
	ds_read_b128 v[146:149], v140
	ds_read_b128 v[150:153], v140 offset:1024
	ds_read_b128 v[154:157], v140 offset:2048
	ds_read_b128 v[158:161], v140 offset:3072
	s_cmp_eq_u32 s82, 12
	s_cselect_b32 s23, s12, s19
	s_cselect_b32 s22, s29, s18
	s_cselect_b32 s19, s9, s79
	s_cselect_b32 s18, s34, s61
	v_lshl_add_u64 v[140:141], s[16:17], 0, v[138:139]
	s_add_i32 m0, s15, 0xc000
	ds_read_b128 v[162:165], v145
	ds_read_b128 v[166:169], v145 offset:1024
	ds_read_b128 v[170:173], v145 offset:2048
	ds_read_b128 v[174:177], v145 offset:3072
	ds_read_b128 v[178:181], v145 offset:4096
	ds_read_b128 v[182:185], v145 offset:5120
	ds_read_b128 v[186:189], v145 offset:6144
	ds_read_b128 v[190:193], v145 offset:7168
	global_load_lds_dwordx4 v[140:141], off
	v_lshl_add_u64 v[140:141], s[16:17], 0, v[136:137]
	s_add_i32 m0, s15, 0xe000
	s_nop 0
	global_load_lds_dwordx4 v[140:141], off
	s_waitcnt lgkmcnt(8)
	s_barrier
	s_waitcnt lgkmcnt(0)
	s_waitcnt lgkmcnt(0)
	v_mfma_f32_16x16x32_bf16 v[126:129], v[146:149], v[162:165], v[126:129]
	v_mfma_f32_16x16x32_bf16 v[118:121], v[154:157], v[162:165], v[118:121]
	v_mfma_f32_16x16x32_bf16 v[110:113], v[146:149], v[170:173], v[110:113]
	v_mfma_f32_16x16x32_bf16 v[102:105], v[154:157], v[170:173], v[102:105]
	v_mfma_f32_16x16x32_bf16 v[94:97], v[146:149], v[178:181], v[94:97]
	v_mfma_f32_16x16x32_bf16 v[86:89], v[154:157], v[178:181], v[86:89]
	v_mfma_f32_16x16x32_bf16 v[78:81], v[146:149], v[186:189], v[78:81]
	v_mfma_f32_16x16x32_bf16 v[70:73], v[154:157], v[186:189], v[70:73]
	v_mfma_f32_16x16x32_bf16 v[126:129], v[150:153], v[166:169], v[126:129]
	v_mfma_f32_16x16x32_bf16 v[118:121], v[158:161], v[166:169], v[118:121]
	v_mfma_f32_16x16x32_bf16 v[110:113], v[150:153], v[174:177], v[110:113]
	v_mfma_f32_16x16x32_bf16 v[102:105], v[158:161], v[174:177], v[102:105]
	v_mfma_f32_16x16x32_bf16 v[94:97], v[150:153], v[182:185], v[94:97]
	v_mfma_f32_16x16x32_bf16 v[86:89], v[158:161], v[182:185], v[86:89]
	v_mfma_f32_16x16x32_bf16 v[78:81], v[150:153], v[190:193], v[78:81]
	v_mfma_f32_16x16x32_bf16 v[70:73], v[158:161], v[190:193], v[70:73]
	s_barrier
	s_add_i32 s86, 0, 0x14000
	v_add_u32_e32 v140, s86, v143
	s_add_i32 s83, s83, s51
	ds_read_b128 v[194:197], v140
	ds_read_b128 v[208:211], v140 offset:1024
	ds_read_b128 v[212:215], v140 offset:2048
	ds_read_b128 v[216:219], v140 offset:3072
	v_lshl_add_u64 v[140:141], s[18:19], 0, v[16:17]
	s_mov_b32 m0, s83
	v_lshl_add_u64 v[220:221], s[18:19], 0, v[130:131]
	global_load_lds_dwordx4 v[140:141], off
	s_add_i32 m0, s83, 0x2000
	s_nop 0
	global_load_lds_dwordx4 v[220:221], off
	s_barrier
	s_waitcnt lgkmcnt(0)
	s_waitcnt lgkmcnt(0)
	v_mfma_f32_16x16x32_bf16 v[122:125], v[194:197], v[162:165], v[122:125]
	v_mfma_f32_16x16x32_bf16 v[114:117], v[212:215], v[162:165], v[114:117]
	v_mfma_f32_16x16x32_bf16 v[106:109], v[194:197], v[170:173], v[106:109]
	v_mfma_f32_16x16x32_bf16 v[98:101], v[212:215], v[170:173], v[98:101]
	v_mfma_f32_16x16x32_bf16 v[90:93], v[194:197], v[178:181], v[90:93]
	v_mfma_f32_16x16x32_bf16 v[82:85], v[212:215], v[178:181], v[82:85]
	v_mfma_f32_16x16x32_bf16 v[74:77], v[194:197], v[186:189], v[74:77]
	v_mfma_f32_16x16x32_bf16 v[66:69], v[212:215], v[186:189], v[66:69]
	v_mfma_f32_16x16x32_bf16 v[122:125], v[208:211], v[166:169], v[122:125]
	v_mfma_f32_16x16x32_bf16 v[114:117], v[216:219], v[166:169], v[114:117]
	v_mfma_f32_16x16x32_bf16 v[106:109], v[208:211], v[174:177], v[106:109]
	v_mfma_f32_16x16x32_bf16 v[98:101], v[216:219], v[174:177], v[98:101]
	v_mfma_f32_16x16x32_bf16 v[90:93], v[208:211], v[182:185], v[90:93]
	v_mfma_f32_16x16x32_bf16 v[82:85], v[216:219], v[182:185], v[82:85]
	v_mfma_f32_16x16x32_bf16 v[74:77], v[208:211], v[190:193], v[74:77]
	v_mfma_f32_16x16x32_bf16 v[66:69], v[216:219], v[190:193], v[66:69]
	s_mov_b32 m0, s15
	v_lshl_add_u64 v[222:223], s[22:23], 0, v[134:135]
	s_barrier
	ds_read_b128 v[162:165], v145 offset:16384
	ds_read_b128 v[166:169], v145 offset:17408
	ds_read_b128 v[170:173], v145 offset:18432
	ds_read_b128 v[174:177], v145 offset:19456
	ds_read_b128 v[178:181], v145 offset:20480
	ds_read_b128 v[182:185], v145 offset:21504
	ds_read_b128 v[186:189], v145 offset:22528
	ds_read_b128 v[190:193], v145 offset:23552
	global_load_lds_dwordx4 v[222:223], off
	v_lshl_add_u64 v[224:225], s[22:23], 0, v[132:133]
	s_mov_b32 m0, s54
	s_nop 0
	global_load_lds_dwordx4 v[224:225], off
	s_barrier
	s_waitcnt lgkmcnt(0)
	s_waitcnt lgkmcnt(0)
	v_mfma_f32_16x16x32_bf16 v[62:65], v[146:149], v[162:165], v[62:65]
	v_mfma_f32_16x16x32_bf16 v[54:57], v[154:157], v[162:165], v[54:57]
	v_mfma_f32_16x16x32_bf16 v[46:49], v[146:149], v[170:173], v[46:49]
	v_mfma_f32_16x16x32_bf16 v[38:41], v[154:157], v[170:173], v[38:41]
	v_mfma_f32_16x16x32_bf16 v[30:33], v[146:149], v[178:181], v[30:33]
	v_mfma_f32_16x16x32_bf16 v[22:25], v[154:157], v[178:181], v[22:25]
	v_mfma_f32_16x16x32_bf16 v[12:15], v[146:149], v[186:189], v[12:15]
	v_mfma_f32_16x16x32_bf16 v[4:7], v[154:157], v[186:189], v[4:7]
	v_mfma_f32_16x16x32_bf16 v[62:65], v[150:153], v[166:169], v[62:65]
	v_mfma_f32_16x16x32_bf16 v[54:57], v[158:161], v[166:169], v[54:57]
	v_mfma_f32_16x16x32_bf16 v[46:49], v[150:153], v[174:177], v[46:49]
	v_mfma_f32_16x16x32_bf16 v[38:41], v[158:161], v[174:177], v[38:41]
	v_mfma_f32_16x16x32_bf16 v[30:33], v[150:153], v[182:185], v[30:33]
	v_mfma_f32_16x16x32_bf16 v[22:25], v[158:161], v[182:185], v[22:25]
	v_mfma_f32_16x16x32_bf16 v[12:15], v[150:153], v[190:193], v[12:15]
	v_mfma_f32_16x16x32_bf16 v[4:7], v[158:161], v[190:193], v[4:7]
	s_barrier
	s_add_u32 s84, s18, 0x40000
	s_addc_u32 s85, s19, 0
	s_add_i32 s83, s86, s51
	v_lshl_add_u64 v[146:147], s[84:85], 0, v[16:17]
	s_mov_b32 m0, s83
	s_nop 0
	global_load_lds_dwordx4 v[146:147], off
	v_lshl_add_u64 v[146:147], s[84:85], 0, v[130:131]
	s_add_i32 m0, s83, 0x2000
	s_nop 0
	global_load_lds_dwordx4 v[146:147], off
	s_waitcnt vmcnt(6)
	s_barrier
	v_mfma_f32_16x16x32_bf16 v[58:61], v[194:197], v[162:165], v[58:61]
	v_mfma_f32_16x16x32_bf16 v[50:53], v[212:215], v[162:165], v[50:53]
	v_mfma_f32_16x16x32_bf16 v[42:45], v[194:197], v[170:173], v[42:45]
	v_mfma_f32_16x16x32_bf16 v[34:37], v[212:215], v[170:173], v[34:37]
	v_mfma_f32_16x16x32_bf16 v[26:29], v[194:197], v[178:181], v[26:29]
	v_mfma_f32_16x16x32_bf16 v[18:21], v[212:215], v[178:181], v[18:21]
	v_mfma_f32_16x16x32_bf16 v[8:11], v[194:197], v[186:189], v[8:11]
	v_mfma_f32_16x16x32_bf16 v[0:3], v[212:215], v[186:189], v[0:3]
	v_mfma_f32_16x16x32_bf16 v[58:61], v[208:211], v[166:169], v[58:61]
	v_mfma_f32_16x16x32_bf16 v[50:53], v[216:219], v[166:169], v[50:53]
	v_mfma_f32_16x16x32_bf16 v[42:45], v[208:211], v[174:177], v[42:45]
	v_mfma_f32_16x16x32_bf16 v[34:37], v[216:219], v[174:177], v[34:37]
	v_mfma_f32_16x16x32_bf16 v[26:29], v[208:211], v[182:185], v[26:29]
	v_mfma_f32_16x16x32_bf16 v[18:21], v[216:219], v[182:185], v[18:21]
	v_mfma_f32_16x16x32_bf16 v[8:11], v[208:211], v[190:193], v[8:11]
	v_mfma_f32_16x16x32_bf16 v[0:3], v[216:219], v[190:193], v[0:3]
	s_add_i32 s83, 0, 0x18000
	v_add_u32_e32 v158, s83, v143
	s_barrier
	ds_read_b128 v[146:149], v158
	ds_read_b128 v[150:153], v158 offset:1024
	ds_read_b128 v[154:157], v158 offset:2048
	ds_read_b128 v[158:161], v158 offset:3072
	s_add_u32 s22, s22, 0x40000
	s_addc_u32 s23, s23, 0
	s_mov_b32 m0, s55
	v_lshl_add_u64 v[194:195], s[22:23], 0, v[134:135]
	ds_read_b128 v[162:165], v145 offset:32768
	ds_read_b128 v[166:169], v145 offset:33792
	ds_read_b128 v[170:173], v145 offset:34816
	ds_read_b128 v[174:177], v145 offset:35840
	ds_read_b128 v[178:181], v145 offset:36864
	ds_read_b128 v[182:185], v145 offset:37888
	ds_read_b128 v[186:189], v145 offset:38912
	ds_read_b128 v[190:193], v145 offset:39936
	global_load_lds_dwordx4 v[194:195], off
	v_lshl_add_u64 v[194:195], s[22:23], 0, v[132:133]
	s_mov_b32 m0, s56
	s_nop 0
	global_load_lds_dwordx4 v[194:195], off
	s_waitcnt lgkmcnt(8)
	s_barrier
	s_waitcnt lgkmcnt(0)
	s_waitcnt lgkmcnt(0)
	v_mfma_f32_16x16x32_bf16 v[126:129], v[146:149], v[162:165], v[126:129]
	v_mfma_f32_16x16x32_bf16 v[118:121], v[154:157], v[162:165], v[118:121]
	v_mfma_f32_16x16x32_bf16 v[110:113], v[146:149], v[170:173], v[110:113]
	v_mfma_f32_16x16x32_bf16 v[102:105], v[154:157], v[170:173], v[102:105]
	v_mfma_f32_16x16x32_bf16 v[94:97], v[146:149], v[178:181], v[94:97]
	v_mfma_f32_16x16x32_bf16 v[86:89], v[154:157], v[178:181], v[86:89]
	v_mfma_f32_16x16x32_bf16 v[78:81], v[146:149], v[186:189], v[78:81]
	v_mfma_f32_16x16x32_bf16 v[70:73], v[154:157], v[186:189], v[70:73]
	v_mfma_f32_16x16x32_bf16 v[126:129], v[150:153], v[166:169], v[126:129]
	v_mfma_f32_16x16x32_bf16 v[118:121], v[158:161], v[166:169], v[118:121]
	v_mfma_f32_16x16x32_bf16 v[110:113], v[150:153], v[174:177], v[110:113]
	v_mfma_f32_16x16x32_bf16 v[102:105], v[158:161], v[174:177], v[102:105]
	v_mfma_f32_16x16x32_bf16 v[94:97], v[150:153], v[182:185], v[94:97]
	v_mfma_f32_16x16x32_bf16 v[86:89], v[158:161], v[182:185], v[86:89]
	v_mfma_f32_16x16x32_bf16 v[78:81], v[150:153], v[190:193], v[78:81]
	v_mfma_f32_16x16x32_bf16 v[70:73], v[158:161], v[190:193], v[70:73]
	s_barrier
	s_add_i32 s22, 0, 0x1c000
	s_add_i32 s23, s83, s51
	v_add_u32_e32 v216, s22, v143
	v_lshl_add_u64 v[140:141], v[140:141], 0, s[10:11]
	s_mov_b32 m0, s23
	ds_read_b128 v[194:197], v216
	ds_read_b128 v[208:211], v216 offset:1024
	ds_read_b128 v[212:215], v216 offset:2048
	ds_read_b128 v[216:219], v216 offset:3072
	global_load_lds_dwordx4 v[140:141], off
	v_lshl_add_u64 v[140:141], v[220:221], 0, s[10:11]
	s_add_i32 m0, s23, 0x2000
	s_nop 0
	global_load_lds_dwordx4 v[140:141], off
	s_barrier
	s_waitcnt lgkmcnt(0)
	s_waitcnt lgkmcnt(0)
	v_mfma_f32_16x16x32_bf16 v[122:125], v[194:197], v[162:165], v[122:125]
	v_mfma_f32_16x16x32_bf16 v[114:117], v[212:215], v[162:165], v[114:117]
	v_mfma_f32_16x16x32_bf16 v[106:109], v[194:197], v[170:173], v[106:109]
	v_mfma_f32_16x16x32_bf16 v[98:101], v[212:215], v[170:173], v[98:101]
	v_mfma_f32_16x16x32_bf16 v[90:93], v[194:197], v[178:181], v[90:93]
	v_mfma_f32_16x16x32_bf16 v[82:85], v[212:215], v[178:181], v[82:85]
	v_mfma_f32_16x16x32_bf16 v[74:77], v[194:197], v[186:189], v[74:77]
	v_mfma_f32_16x16x32_bf16 v[66:69], v[212:215], v[186:189], v[66:69]
	v_mfma_f32_16x16x32_bf16 v[122:125], v[208:211], v[166:169], v[122:125]
	v_mfma_f32_16x16x32_bf16 v[114:117], v[216:219], v[166:169], v[114:117]
	v_mfma_f32_16x16x32_bf16 v[106:109], v[208:211], v[174:177], v[106:109]
	v_mfma_f32_16x16x32_bf16 v[98:101], v[216:219], v[174:177], v[98:101]
	v_mfma_f32_16x16x32_bf16 v[90:93], v[208:211], v[182:185], v[90:93]
	v_mfma_f32_16x16x32_bf16 v[82:85], v[216:219], v[182:185], v[82:85]
	v_mfma_f32_16x16x32_bf16 v[74:77], v[208:211], v[190:193], v[74:77]
	v_mfma_f32_16x16x32_bf16 v[66:69], v[216:219], v[190:193], v[66:69]
	s_mov_b32 m0, s57
	v_lshl_add_u64 v[140:141], v[222:223], 0, s[10:11]
	s_barrier
	ds_read_b128 v[162:165], v145 offset:49152
	ds_read_b128 v[166:169], v145 offset:50176
	ds_read_b128 v[170:173], v145 offset:51200
	ds_read_b128 v[174:177], v145 offset:52224
	ds_read_b128 v[178:181], v145 offset:53248
	ds_read_b128 v[182:185], v145 offset:54272
	ds_read_b128 v[186:189], v145 offset:55296
	ds_read_b128 v[190:193], v145 offset:56320
	global_load_lds_dwordx4 v[140:141], off
	v_lshl_add_u64 v[140:141], v[224:225], 0, s[10:11]
	s_mov_b32 m0, s58
	s_nop 0
	global_load_lds_dwordx4 v[140:141], off
	s_barrier
	s_waitcnt lgkmcnt(0)
	s_waitcnt lgkmcnt(0)
	v_mfma_f32_16x16x32_bf16 v[62:65], v[146:149], v[162:165], v[62:65]
	v_mfma_f32_16x16x32_bf16 v[54:57], v[154:157], v[162:165], v[54:57]
	v_mfma_f32_16x16x32_bf16 v[46:49], v[146:149], v[170:173], v[46:49]
	v_mfma_f32_16x16x32_bf16 v[38:41], v[154:157], v[170:173], v[38:41]
	v_mfma_f32_16x16x32_bf16 v[30:33], v[146:149], v[178:181], v[30:33]
	v_mfma_f32_16x16x32_bf16 v[22:25], v[154:157], v[178:181], v[22:25]
	v_mfma_f32_16x16x32_bf16 v[12:15], v[146:149], v[186:189], v[12:15]
	v_mfma_f32_16x16x32_bf16 v[4:7], v[154:157], v[186:189], v[4:7]
	v_mfma_f32_16x16x32_bf16 v[62:65], v[150:153], v[166:169], v[62:65]
	v_mfma_f32_16x16x32_bf16 v[54:57], v[158:161], v[166:169], v[54:57]
	v_mfma_f32_16x16x32_bf16 v[46:49], v[150:153], v[174:177], v[46:49]
	v_mfma_f32_16x16x32_bf16 v[38:41], v[158:161], v[174:177], v[38:41]
	v_mfma_f32_16x16x32_bf16 v[30:33], v[150:153], v[182:185], v[30:33]
	v_mfma_f32_16x16x32_bf16 v[22:25], v[158:161], v[182:185], v[22:25]
	v_mfma_f32_16x16x32_bf16 v[12:15], v[150:153], v[190:193], v[12:15]
	v_mfma_f32_16x16x32_bf16 v[4:7], v[158:161], v[190:193], v[4:7]
	s_barrier
	s_add_u32 s18, s18, 0x40080
	s_addc_u32 s19, s19, 0
	s_add_i32 s22, s22, s51
	v_lshl_add_u64 v[140:141], s[18:19], 0, v[16:17]
	s_mov_b32 m0, s22
	s_nop 0
	global_load_lds_dwordx4 v[140:141], off
	v_lshl_add_u64 v[140:141], s[18:19], 0, v[130:131]
	s_add_i32 m0, s22, 0x2000
	s_nop 0
	global_load_lds_dwordx4 v[140:141], off
	s_waitcnt vmcnt(6)
	s_barrier
	v_mfma_f32_16x16x32_bf16 v[58:61], v[194:197], v[162:165], v[58:61]
	v_mfma_f32_16x16x32_bf16 v[50:53], v[212:215], v[162:165], v[50:53]
	v_mfma_f32_16x16x32_bf16 v[42:45], v[194:197], v[170:173], v[42:45]
	v_mfma_f32_16x16x32_bf16 v[34:37], v[212:215], v[170:173], v[34:37]
	v_mfma_f32_16x16x32_bf16 v[26:29], v[194:197], v[178:181], v[26:29]
	v_mfma_f32_16x16x32_bf16 v[18:21], v[212:215], v[178:181], v[18:21]
	v_mfma_f32_16x16x32_bf16 v[8:11], v[194:197], v[186:189], v[8:11]
	v_mfma_f32_16x16x32_bf16 v[0:3], v[212:215], v[186:189], v[0:3]
	v_mfma_f32_16x16x32_bf16 v[58:61], v[208:211], v[166:169], v[58:61]
	v_mfma_f32_16x16x32_bf16 v[50:53], v[216:219], v[166:169], v[50:53]
	v_mfma_f32_16x16x32_bf16 v[42:45], v[208:211], v[174:177], v[42:45]
	v_mfma_f32_16x16x32_bf16 v[34:37], v[216:219], v[174:177], v[34:37]
	v_mfma_f32_16x16x32_bf16 v[26:29], v[208:211], v[182:185], v[26:29]
	v_mfma_f32_16x16x32_bf16 v[18:21], v[216:219], v[182:185], v[18:21]
	v_mfma_f32_16x16x32_bf16 v[8:11], v[208:211], v[190:193], v[8:11]
	v_mfma_f32_16x16x32_bf16 v[0:3], v[216:219], v[190:193], v[0:3]
	s_add_i32 s82, s82, 2
	s_add_u32 s61, s61, 0x100
	s_addc_u32 s79, s79, 0
	s_add_u32 s16, s16, 0x100
	s_addc_u32 s17, s17, 0
	s_cmp_gt_u32 s82, 13
	s_barrier
	s_cbranch_scc0 .LBB0_147
	v_mul_f32_e32 v208, 0xbfb8aa3b, v126
	v_mul_f32_e32 v209, 0xbfb8aa3b, v127
	v_mul_f32_e32 v210, 0xbfb8aa3b, v128
	v_mul_f32_e32 v211, 0xbfb8aa3b, v129
	v_mul_f32_e32 v212, 0xbfb8aa3b, v118
	v_mul_f32_e32 v213, 0xbfb8aa3b, v119
	v_mul_f32_e32 v214, 0xbfb8aa3b, v120
	v_mul_f32_e32 v215, 0xbfb8aa3b, v121
	v_exp_f32_e32 v208, v208
	v_exp_f32_e32 v209, v209
	v_exp_f32_e32 v210, v210
	v_exp_f32_e32 v211, v211
	v_exp_f32_e32 v212, v212
	v_exp_f32_e32 v213, v213
	v_exp_f32_e32 v214, v214
	v_exp_f32_e32 v215, v215
	v_add_f32_e32 v208, 1.0, v208
	v_add_f32_e32 v209, 1.0, v209
	v_add_f32_e32 v210, 1.0, v210
	v_add_f32_e32 v211, 1.0, v211
	v_add_f32_e32 v212, 1.0, v212
	v_add_f32_e32 v213, 1.0, v213
	v_add_f32_e32 v214, 1.0, v214
	v_add_f32_e32 v215, 1.0, v215
	v_rcp_f32_e32 v208, v208
	v_rcp_f32_e32 v209, v209
	v_rcp_f32_e32 v210, v210
	v_rcp_f32_e32 v211, v211
	v_rcp_f32_e32 v212, v212
	v_rcp_f32_e32 v213, v213
	v_rcp_f32_e32 v214, v214
	v_rcp_f32_e32 v215, v215
	v_mul_f32_e32 v216, v126, v208
	v_mul_f32_e32 v217, v127, v209
	v_mul_f32_e32 v218, v128, v210
	v_mul_f32_e32 v219, v129, v211
	v_mul_f32_e32 v220, v118, v212
	v_mul_f32_e32 v221, v119, v213
	v_mul_f32_e32 v222, v120, v214
	v_mul_f32_e32 v223, v121, v215
	v_mul_f32_e32 v216, v216, v122
	v_mul_f32_e32 v217, v217, v123
	v_mul_f32_e32 v218, v218, v124
	v_mul_f32_e32 v219, v219, v125
	v_mul_f32_e32 v220, v220, v114
	v_mul_f32_e32 v221, v221, v115
	v_mul_f32_e32 v222, v222, v116
	v_mul_f32_e32 v223, v223, v117
	v_lshl_or_b32 v148, s2, 7, v144
	v_lshl_add_u32 v146, s14, 8, v142
	v_ashrrev_i32_e32 v149, 31, v148
	v_mov_b64_e32 v[140:141], s[94:95]
	v_mad_i64_i32 v[150:151], s[16:17], v146, s65, v[140:141]
	v_lshlrev_b64 v[114:115], 1, v[148:149]
	v_lshl_add_u64 v[120:121], v[150:151], 0, v[114:115]
	v_cvt_pk_bf16_f32 v116, v216, v217
	v_cvt_pk_bf16_f32 v117, v218, v219
	v_cvt_pk_bf16_f32 v118, v220, v221
	v_cvt_pk_bf16_f32 v119, v222, v223
	global_store_dwordx4 v[120:121], v[116:119], off
	v_mul_f32_e32 v208, 0xbfb8aa3b, v110
	v_mul_f32_e32 v209, 0xbfb8aa3b, v111
	v_mul_f32_e32 v210, 0xbfb8aa3b, v112
	v_mul_f32_e32 v211, 0xbfb8aa3b, v113
	v_mul_f32_e32 v212, 0xbfb8aa3b, v102
	v_mul_f32_e32 v213, 0xbfb8aa3b, v103
	v_mul_f32_e32 v214, 0xbfb8aa3b, v104
	v_mul_f32_e32 v215, 0xbfb8aa3b, v105
	v_exp_f32_e32 v208, v208
	v_exp_f32_e32 v209, v209
	v_exp_f32_e32 v210, v210
	v_exp_f32_e32 v211, v211
	v_exp_f32_e32 v212, v212
	v_exp_f32_e32 v213, v213
	v_exp_f32_e32 v214, v214
	v_exp_f32_e32 v215, v215
	v_add_f32_e32 v208, 1.0, v208
	v_add_f32_e32 v209, 1.0, v209
	v_add_f32_e32 v210, 1.0, v210
	v_add_f32_e32 v211, 1.0, v211
	v_add_f32_e32 v212, 1.0, v212
	v_add_f32_e32 v213, 1.0, v213
	v_add_f32_e32 v214, 1.0, v214
	v_add_f32_e32 v215, 1.0, v215
	v_rcp_f32_e32 v208, v208
	v_rcp_f32_e32 v209, v209
	v_rcp_f32_e32 v210, v210
	v_rcp_f32_e32 v211, v211
	v_rcp_f32_e32 v212, v212
	v_rcp_f32_e32 v213, v213
	v_rcp_f32_e32 v214, v214
	v_rcp_f32_e32 v215, v215
	v_mul_f32_e32 v216, v110, v208
	v_mul_f32_e32 v217, v111, v209
	v_mul_f32_e32 v218, v112, v210
	v_mul_f32_e32 v219, v113, v211
	v_mul_f32_e32 v220, v102, v212
	v_mul_f32_e32 v221, v103, v213
	v_mul_f32_e32 v222, v104, v214
	v_mul_f32_e32 v223, v105, v215
	v_mul_f32_e32 v216, v216, v106
	v_mul_f32_e32 v217, v217, v107
	v_mul_f32_e32 v218, v218, v108
	v_mul_f32_e32 v219, v219, v109
	v_mul_f32_e32 v220, v220, v98
	v_mul_f32_e32 v221, v221, v99
	v_mul_f32_e32 v222, v222, v100
	v_mul_f32_e32 v223, v223, v101
	v_or_b32_e32 v116, 16, v146
	v_mad_i64_i32 v[116:117], s[16:17], v116, s65, v[140:141]
	v_lshl_add_u64 v[102:103], v[116:117], 0, v[114:115]
	v_cvt_pk_bf16_f32 v98, v216, v217
	v_cvt_pk_bf16_f32 v99, v218, v219
	v_cvt_pk_bf16_f32 v100, v220, v221
	v_cvt_pk_bf16_f32 v101, v222, v223
	global_store_dwordx4 v[102:103], v[98:101], off
	v_mul_f32_e32 v208, 0xbfb8aa3b, v94
	v_mul_f32_e32 v209, 0xbfb8aa3b, v95
	v_mul_f32_e32 v210, 0xbfb8aa3b, v96
	v_mul_f32_e32 v211, 0xbfb8aa3b, v97
	v_mul_f32_e32 v212, 0xbfb8aa3b, v86
	v_mul_f32_e32 v213, 0xbfb8aa3b, v87
	v_mul_f32_e32 v214, 0xbfb8aa3b, v88
	v_mul_f32_e32 v215, 0xbfb8aa3b, v89
	v_exp_f32_e32 v208, v208
	v_exp_f32_e32 v209, v209
	v_exp_f32_e32 v210, v210
	v_exp_f32_e32 v211, v211
	v_exp_f32_e32 v212, v212
	v_exp_f32_e32 v213, v213
	v_exp_f32_e32 v214, v214
	v_exp_f32_e32 v215, v215
	v_add_f32_e32 v208, 1.0, v208
	v_add_f32_e32 v209, 1.0, v209
	v_add_f32_e32 v210, 1.0, v210
	v_add_f32_e32 v211, 1.0, v211
	v_add_f32_e32 v212, 1.0, v212
	v_add_f32_e32 v213, 1.0, v213
	v_add_f32_e32 v214, 1.0, v214
	v_add_f32_e32 v215, 1.0, v215
	v_rcp_f32_e32 v208, v208
	v_rcp_f32_e32 v209, v209
	v_rcp_f32_e32 v210, v210
	v_rcp_f32_e32 v211, v211
	v_rcp_f32_e32 v212, v212
	v_rcp_f32_e32 v213, v213
	v_rcp_f32_e32 v214, v214
	v_rcp_f32_e32 v215, v215
	v_mul_f32_e32 v216, v94, v208
	v_mul_f32_e32 v217, v95, v209
	v_mul_f32_e32 v218, v96, v210
	v_mul_f32_e32 v219, v97, v211
	v_mul_f32_e32 v220, v86, v212
	v_mul_f32_e32 v221, v87, v213
	v_mul_f32_e32 v222, v88, v214
	v_mul_f32_e32 v223, v89, v215
	v_mul_f32_e32 v216, v216, v90
	v_mul_f32_e32 v217, v217, v91
	v_mul_f32_e32 v218, v218, v92
	v_mul_f32_e32 v219, v219, v93
	v_mul_f32_e32 v220, v220, v82
	v_mul_f32_e32 v221, v221, v83
	v_mul_f32_e32 v222, v222, v84
	v_mul_f32_e32 v223, v223, v85
	v_or_b32_e32 v98, 32, v146
	v_mad_i64_i32 v[98:99], s[16:17], v98, s65, v[140:141]
	v_lshl_add_u64 v[86:87], v[98:99], 0, v[114:115]
	v_cvt_pk_bf16_f32 v82, v216, v217
	v_cvt_pk_bf16_f32 v83, v218, v219
	v_cvt_pk_bf16_f32 v84, v220, v221
	v_cvt_pk_bf16_f32 v85, v222, v223
	global_store_dwordx4 v[86:87], v[82:85], off
	v_mul_f32_e32 v208, 0xbfb8aa3b, v78
	v_mul_f32_e32 v209, 0xbfb8aa3b, v79
	v_mul_f32_e32 v210, 0xbfb8aa3b, v80
	v_mul_f32_e32 v211, 0xbfb8aa3b, v81
	v_mul_f32_e32 v212, 0xbfb8aa3b, v70
	v_mul_f32_e32 v213, 0xbfb8aa3b, v71
	v_mul_f32_e32 v214, 0xbfb8aa3b, v72
	v_mul_f32_e32 v215, 0xbfb8aa3b, v73
	v_exp_f32_e32 v208, v208
	v_exp_f32_e32 v209, v209
	v_exp_f32_e32 v210, v210
	v_exp_f32_e32 v211, v211
	v_exp_f32_e32 v212, v212
	v_exp_f32_e32 v213, v213
	v_exp_f32_e32 v214, v214
	v_exp_f32_e32 v215, v215
	v_add_f32_e32 v208, 1.0, v208
	v_add_f32_e32 v209, 1.0, v209
	v_add_f32_e32 v210, 1.0, v210
	v_add_f32_e32 v211, 1.0, v211
	v_add_f32_e32 v212, 1.0, v212
	v_add_f32_e32 v213, 1.0, v213
	v_add_f32_e32 v214, 1.0, v214
	v_add_f32_e32 v215, 1.0, v215
	v_rcp_f32_e32 v208, v208
	v_rcp_f32_e32 v209, v209
	v_rcp_f32_e32 v210, v210
	v_rcp_f32_e32 v211, v211
	v_rcp_f32_e32 v212, v212
	v_rcp_f32_e32 v213, v213
	v_rcp_f32_e32 v214, v214
	v_rcp_f32_e32 v215, v215
	v_mul_f32_e32 v216, v78, v208
	v_mul_f32_e32 v217, v79, v209
	v_mul_f32_e32 v218, v80, v210
	v_mul_f32_e32 v219, v81, v211
	v_mul_f32_e32 v220, v70, v212
	v_mul_f32_e32 v221, v71, v213
	v_mul_f32_e32 v222, v72, v214
	v_mul_f32_e32 v223, v73, v215
	v_mul_f32_e32 v216, v216, v74
	v_mul_f32_e32 v217, v217, v75
	v_mul_f32_e32 v218, v218, v76
	v_mul_f32_e32 v219, v219, v77
	v_mul_f32_e32 v220, v220, v66
	v_mul_f32_e32 v221, v221, v67
	v_mul_f32_e32 v222, v222, v68
	v_mul_f32_e32 v223, v223, v69
	v_or_b32_e32 v82, 48, v146
	v_mad_i64_i32 v[82:83], s[16:17], v82, s65, v[140:141]
	v_lshl_add_u64 v[70:71], v[82:83], 0, v[114:115]
	v_cvt_pk_bf16_f32 v66, v216, v217
	v_cvt_pk_bf16_f32 v67, v218, v219
	v_cvt_pk_bf16_f32 v68, v220, v221
	v_cvt_pk_bf16_f32 v69, v222, v223
	global_store_dwordx4 v[70:71], v[66:69], off
	v_mul_f32_e32 v208, 0xbfb8aa3b, v62
	v_mul_f32_e32 v209, 0xbfb8aa3b, v63
	v_mul_f32_e32 v210, 0xbfb8aa3b, v64
	v_mul_f32_e32 v211, 0xbfb8aa3b, v65
	v_mul_f32_e32 v212, 0xbfb8aa3b, v54
	v_mul_f32_e32 v213, 0xbfb8aa3b, v55
	v_mul_f32_e32 v214, 0xbfb8aa3b, v56
	v_mul_f32_e32 v215, 0xbfb8aa3b, v57
	v_exp_f32_e32 v208, v208
	v_exp_f32_e32 v209, v209
	v_exp_f32_e32 v210, v210
	v_exp_f32_e32 v211, v211
	v_exp_f32_e32 v212, v212
	v_exp_f32_e32 v213, v213
	v_exp_f32_e32 v214, v214
	v_exp_f32_e32 v215, v215
	v_add_f32_e32 v208, 1.0, v208
	v_add_f32_e32 v209, 1.0, v209
	v_add_f32_e32 v210, 1.0, v210
	v_add_f32_e32 v211, 1.0, v211
	v_add_f32_e32 v212, 1.0, v212
	v_add_f32_e32 v213, 1.0, v213
	v_add_f32_e32 v214, 1.0, v214
	v_add_f32_e32 v215, 1.0, v215
	v_rcp_f32_e32 v208, v208
	v_rcp_f32_e32 v209, v209
	v_rcp_f32_e32 v210, v210
	v_rcp_f32_e32 v211, v211
	v_rcp_f32_e32 v212, v212
	v_rcp_f32_e32 v213, v213
	v_rcp_f32_e32 v214, v214
	v_rcp_f32_e32 v215, v215
	v_mul_f32_e32 v216, v62, v208
	v_mul_f32_e32 v217, v63, v209
	v_mul_f32_e32 v218, v64, v210
	v_mul_f32_e32 v219, v65, v211
	v_mul_f32_e32 v220, v54, v212
	v_mul_f32_e32 v221, v55, v213
	v_mul_f32_e32 v222, v56, v214
	v_mul_f32_e32 v223, v57, v215
	v_mul_f32_e32 v216, v216, v58
	v_mul_f32_e32 v217, v217, v59
	v_mul_f32_e32 v218, v218, v60
	v_mul_f32_e32 v219, v219, v61
	v_mul_f32_e32 v220, v220, v50
	v_mul_f32_e32 v221, v221, v51
	v_mul_f32_e32 v222, v222, v52
	v_mul_f32_e32 v223, v223, v53
	v_add_u32_e32 v66, 0x80, v146
	v_mad_i64_i32 v[66:67], s[16:17], v66, s65, v[140:141]
	v_lshl_add_u64 v[54:55], v[66:67], 0, v[114:115]
	v_cvt_pk_bf16_f32 v50, v216, v217
	v_cvt_pk_bf16_f32 v51, v218, v219
	v_cvt_pk_bf16_f32 v52, v220, v221
	v_cvt_pk_bf16_f32 v53, v222, v223
	global_store_dwordx4 v[54:55], v[50:53], off
	v_mul_f32_e32 v208, 0xbfb8aa3b, v46
	v_mul_f32_e32 v209, 0xbfb8aa3b, v47
	v_mul_f32_e32 v210, 0xbfb8aa3b, v48
	v_mul_f32_e32 v211, 0xbfb8aa3b, v49
	v_mul_f32_e32 v212, 0xbfb8aa3b, v38
	v_mul_f32_e32 v213, 0xbfb8aa3b, v39
	v_mul_f32_e32 v214, 0xbfb8aa3b, v40
	v_mul_f32_e32 v215, 0xbfb8aa3b, v41
	v_exp_f32_e32 v208, v208
	v_exp_f32_e32 v209, v209
	v_exp_f32_e32 v210, v210
	v_exp_f32_e32 v211, v211
	v_exp_f32_e32 v212, v212
	v_exp_f32_e32 v213, v213
	v_exp_f32_e32 v214, v214
	v_exp_f32_e32 v215, v215
	v_add_f32_e32 v208, 1.0, v208
	v_add_f32_e32 v209, 1.0, v209
	v_add_f32_e32 v210, 1.0, v210
	v_add_f32_e32 v211, 1.0, v211
	v_add_f32_e32 v212, 1.0, v212
	v_add_f32_e32 v213, 1.0, v213
	v_add_f32_e32 v214, 1.0, v214
	v_add_f32_e32 v215, 1.0, v215
	v_rcp_f32_e32 v208, v208
	v_rcp_f32_e32 v209, v209
	v_rcp_f32_e32 v210, v210
	v_rcp_f32_e32 v211, v211
	v_rcp_f32_e32 v212, v212
	v_rcp_f32_e32 v213, v213
	v_rcp_f32_e32 v214, v214
	v_rcp_f32_e32 v215, v215
	v_mul_f32_e32 v216, v46, v208
	v_mul_f32_e32 v217, v47, v209
	v_mul_f32_e32 v218, v48, v210
	v_mul_f32_e32 v219, v49, v211
	v_mul_f32_e32 v220, v38, v212
	v_mul_f32_e32 v221, v39, v213
	v_mul_f32_e32 v222, v40, v214
	v_mul_f32_e32 v223, v41, v215
	v_mul_f32_e32 v216, v216, v42
	v_mul_f32_e32 v217, v217, v43
	v_mul_f32_e32 v218, v218, v44
	v_mul_f32_e32 v219, v219, v45
	v_mul_f32_e32 v220, v220, v34
	v_mul_f32_e32 v221, v221, v35
	v_mul_f32_e32 v222, v222, v36
	v_mul_f32_e32 v223, v223, v37
	v_add_u32_e32 v50, 0x90, v146
	v_mad_i64_i32 v[50:51], s[16:17], v50, s65, v[140:141]
	v_lshl_add_u64 v[38:39], v[50:51], 0, v[114:115]
	v_cvt_pk_bf16_f32 v34, v216, v217
	v_cvt_pk_bf16_f32 v35, v218, v219
	v_cvt_pk_bf16_f32 v36, v220, v221
	v_cvt_pk_bf16_f32 v37, v222, v223
	global_store_dwordx4 v[38:39], v[34:37], off
	v_mul_f32_e32 v208, 0xbfb8aa3b, v30
	v_mul_f32_e32 v209, 0xbfb8aa3b, v31
	v_mul_f32_e32 v210, 0xbfb8aa3b, v32
	v_mul_f32_e32 v211, 0xbfb8aa3b, v33
	v_mul_f32_e32 v212, 0xbfb8aa3b, v22
	v_mul_f32_e32 v213, 0xbfb8aa3b, v23
	v_mul_f32_e32 v214, 0xbfb8aa3b, v24
	v_mul_f32_e32 v215, 0xbfb8aa3b, v25
	v_exp_f32_e32 v208, v208
	v_exp_f32_e32 v209, v209
	v_exp_f32_e32 v210, v210
	v_exp_f32_e32 v211, v211
	v_exp_f32_e32 v212, v212
	v_exp_f32_e32 v213, v213
	v_exp_f32_e32 v214, v214
	v_exp_f32_e32 v215, v215
	v_add_f32_e32 v208, 1.0, v208
	v_add_f32_e32 v209, 1.0, v209
	v_add_f32_e32 v210, 1.0, v210
	v_add_f32_e32 v211, 1.0, v211
	v_add_f32_e32 v212, 1.0, v212
	v_add_f32_e32 v213, 1.0, v213
	v_add_f32_e32 v214, 1.0, v214
	v_add_f32_e32 v215, 1.0, v215
	v_rcp_f32_e32 v208, v208
	v_rcp_f32_e32 v209, v209
	v_rcp_f32_e32 v210, v210
	v_rcp_f32_e32 v211, v211
	v_rcp_f32_e32 v212, v212
	v_rcp_f32_e32 v213, v213
	v_rcp_f32_e32 v214, v214
	v_rcp_f32_e32 v215, v215
	v_mul_f32_e32 v216, v30, v208
	v_mul_f32_e32 v217, v31, v209
	v_mul_f32_e32 v218, v32, v210
	v_mul_f32_e32 v219, v33, v211
	v_mul_f32_e32 v220, v22, v212
	v_mul_f32_e32 v221, v23, v213
	v_mul_f32_e32 v222, v24, v214
	v_mul_f32_e32 v223, v25, v215
	v_mul_f32_e32 v216, v216, v26
	v_mul_f32_e32 v217, v217, v27
	v_mul_f32_e32 v218, v218, v28
	v_mul_f32_e32 v219, v219, v29
	v_mul_f32_e32 v220, v220, v18
	v_mul_f32_e32 v221, v221, v19
	v_mul_f32_e32 v222, v222, v20
	v_mul_f32_e32 v223, v223, v21
	v_add_u32_e32 v34, 0xa0, v146
	v_mad_i64_i32 v[34:35], s[16:17], v34, s65, v[140:141]
	v_lshl_add_u64 v[22:23], v[34:35], 0, v[114:115]
	v_cvt_pk_bf16_f32 v18, v216, v217
	v_cvt_pk_bf16_f32 v19, v218, v219
	v_cvt_pk_bf16_f32 v20, v220, v221
	v_cvt_pk_bf16_f32 v21, v222, v223
	global_store_dwordx4 v[22:23], v[18:21], off
	v_mul_f32_e32 v208, 0xbfb8aa3b, v12
	v_mul_f32_e32 v209, 0xbfb8aa3b, v13
	v_mul_f32_e32 v210, 0xbfb8aa3b, v14
	v_mul_f32_e32 v211, 0xbfb8aa3b, v15
	v_mul_f32_e32 v212, 0xbfb8aa3b, v4
	v_mul_f32_e32 v213, 0xbfb8aa3b, v5
	v_mul_f32_e32 v214, 0xbfb8aa3b, v6
	v_mul_f32_e32 v215, 0xbfb8aa3b, v7
	v_exp_f32_e32 v208, v208
	v_exp_f32_e32 v209, v209
	v_exp_f32_e32 v210, v210
	v_exp_f32_e32 v211, v211
	v_exp_f32_e32 v212, v212
	v_exp_f32_e32 v213, v213
	v_exp_f32_e32 v214, v214
	v_exp_f32_e32 v215, v215
	v_add_f32_e32 v208, 1.0, v208
	v_add_f32_e32 v209, 1.0, v209
	v_add_f32_e32 v210, 1.0, v210
	v_add_f32_e32 v211, 1.0, v211
	v_add_f32_e32 v212, 1.0, v212
	v_add_f32_e32 v213, 1.0, v213
	v_add_f32_e32 v214, 1.0, v214
	v_add_f32_e32 v215, 1.0, v215
	v_rcp_f32_e32 v208, v208
	v_rcp_f32_e32 v209, v209
	v_rcp_f32_e32 v210, v210
	v_rcp_f32_e32 v211, v211
	v_rcp_f32_e32 v212, v212
	v_rcp_f32_e32 v213, v213
	v_rcp_f32_e32 v214, v214
	v_rcp_f32_e32 v215, v215
	v_mul_f32_e32 v216, v12, v208
	v_mul_f32_e32 v217, v13, v209
	v_mul_f32_e32 v218, v14, v210
	v_mul_f32_e32 v219, v15, v211
	v_mul_f32_e32 v220, v4, v212
	v_mul_f32_e32 v221, v5, v213
	v_mul_f32_e32 v222, v6, v214
	v_mul_f32_e32 v223, v7, v215
	v_mul_f32_e32 v216, v216, v8
	v_mul_f32_e32 v217, v217, v9
	v_mul_f32_e32 v218, v218, v10
	v_mul_f32_e32 v219, v219, v11
	v_mul_f32_e32 v220, v220, v0
	v_mul_f32_e32 v221, v221, v1
	v_mul_f32_e32 v222, v222, v2
	v_mul_f32_e32 v223, v223, v3
	v_add_u32_e32 v18, 0xb0, v146
	v_mad_i64_i32 v[18:19], s[16:17], v18, s65, v[140:141]
	v_lshl_add_u64 v[4:5], v[18:19], 0, v[114:115]
	v_cvt_pk_bf16_f32 v0, v216, v217
	v_cvt_pk_bf16_f32 v1, v218, v219
	v_cvt_pk_bf16_f32 v2, v220, v221
	v_cvt_pk_bf16_f32 v3, v222, v223
	global_store_dwordx4 v[4:5], v[0:3], off
	s_and_b64 vcc, exec, s[38:39]
	s_mov_b32 s2, s8
	s_mov_b32 s14, s28
	s_mov_b64 s[16:17], s[42:43]
	s_mov_b64 s[18:19], s[40:41]
	s_cbranch_vccz .LBB0_144
	s_waitcnt vmcnt(0)
	s_cmpk_gt_u32 s48, 0xff
	s_cbranch_scc1 .LBB0_151
	s_barrier
